# rwkv_fix phase: all 34 loads of an item (fragments and read-modify-write operands) issued up front with counted waits
# speedup vs baseline: 1.0295x; 1.0074x over previous
.LBB0_1291:
	s_and_b32 s0, s6, 0x7c0
	s_ashr_i32 s16, s2, 5
	s_and_b32 s14, s8, 0xfffff000
	v_add_u32_e32 v48, s0, v21
	s_and_b32 s15, s16, 1
	s_addk_i32 s14, 0x1000
	v_add_u32_e32 v45, 0x800, v48
	v_or_b32_e32 v50, v45, v20
	s_cmp_eq_u32 s15, 0
	s_cselect_b64 vcc, -1, 0
	v_sub_u32_e32 v51, 0xfff, v50
	v_cndmask_b32_e32 v52, v51, v50, vcc
	v_add_u32_e32 v50, s14, v52
	s_movk_i32 s0, 0x1520
	v_mad_i64_i32 v[54:55], s[0:1], v50, s0, v[26:27]
	s_and_b32 s0, s2, 0xc0
	s_lshl_b32 s4, s0, 1
	v_lshl_add_u64 v[56:57], v[54:55], 0, s[4:5]
	v_lshl_add_u64 v[54:55], v[56:57], 0, v[22:23]
	s_mov_b64 s[0:1], 0x1320
	v_lshl_add_u64 v[56:57], v[54:55], 0, s[0:1]
	v_add_co_u32_e64 v58, s[0:1], s10, v54
	s_ashr_i32 s17, s16, 31
	s_nop 0
	v_addc_co_u32_e64 v59, s[0:1], 0, v55, s[0:1]
	s_lshl_b64 s[0:1], s[16:17], 14
	s_nop 0
	v_lshl_add_u64 v[54:55], v[24:25], 0, s[0:1]
	global_load_dwordx4 v[60:63], v[58:59], off offset:800
	global_load_dwordx4 v[64:67], v[56:57], off offset:64
	global_load_dwordx4 v[56:59], v[54:55], off
	global_load_dwordx4 v[68:71], v[54:55], off offset:16
	s_mov_b64 s[0:1], 0x1000
	global_load_dwordx4 v[72:75], v[54:55], off offset:128
	global_load_dwordx4 v[76:79], v[54:55], off offset:144
	v_lshl_add_u64 v[80:81], v[54:55], 0, s[0:1]
	v_add_co_u32_e64 v82, s[0:1], s10, v54
	s_nop 1
	v_addc_co_u32_e64 v83, s[0:1], 0, v55, s[0:1]
	s_movk_i32 s0, 0x2000
	s_nop 0
	v_add_co_u32_e64 v84, s[0:1], s0, v54
	s_nop 1
	v_addc_co_u32_e64 v85, s[0:1], 0, v55, s[0:1]
	global_load_dwordx4 v[86:89], v[84:85], off offset:-4096
	global_load_dwordx4 v[90:93], v[80:81], off offset:16
	s_mov_b64 s[0:1], 0x1080
	v_lshl_add_u64 v[80:81], v[54:55], 0, s[0:1]
	global_load_dwordx4 v[94:97], v[82:83], off offset:128
	global_load_dwordx4 v[98:101], v[80:81], off offset:16
	s_mov_b64 s[0:1], 0x2000
	v_lshl_add_u64 v[80:81], v[54:55], 0, s[0:1]
	s_mov_b64 s[0:1], 0x2080
	global_load_dwordx4 v[102:105], v[84:85], off
	global_load_dwordx4 v[106:109], v[80:81], off offset:16
	v_lshl_add_u64 v[80:81], v[54:55], 0, s[0:1]
	global_load_dwordx4 v[110:113], v[84:85], off offset:128
	global_load_dwordx4 v[82:85], v[80:81], off offset:16
	s_mov_b64 s[0:1], 0x3000
	v_lshl_add_u64 v[80:81], v[54:55], 0, s[0:1]
	s_movk_i32 s0, 0x3000
	v_add_co_u32_e64 v114, s[0:1], s0, v54
	s_nop 1
	v_addc_co_u32_e64 v115, s[0:1], 0, v55, s[0:1]
	global_load_dwordx4 v[116:119], v[114:115], off
	global_load_dwordx4 v[120:123], v[80:81], off offset:16
	s_mov_b64 s[0:1], 0x3080
	v_lshl_add_u64 v[80:81], v[54:55], 0, s[0:1]
	s_lshl_b32 s0, s15, 9
	s_add_u32 s0, s22, s0
	s_addc_u32 s1, s23, 0
	s_add_u32 s0, s0, s4
	s_addc_u32 s1, s1, 0
	global_load_dwordx4 v[124:127], v[114:115], off offset:128
	global_load_dwordx4 v[128:131], v[80:81], off offset:16
	v_or_b32_e32 v54, v45, v32
	v_sub_u32_e32 v45, 0xfff, v54
	v_cndmask_b32_e32 v47, v45, v54, vcc
	v_lshl_add_u64 v[80:81], s[0:1], 0, v[28:29]
	v_add_u32_e32 v45, s14, v47
	v_mad_i64_i32 v[114:115], s[0:1], v45, s13, v[80:81]
	global_load_ushort v55, v[114:115], off
	global_load_ushort v132, v[114:115], off offset:32
	global_load_ushort v134, v[114:115], off offset:64
	global_load_ushort v136, v[114:115], off offset:96
	v_or_b32_e32 v138, 1, v54
	v_sub_u32_e32 v45, 0xfff, v138
	v_cndmask_b32_e32 v140, v45, v138, vcc
	v_add_u32_e32 v142, s14, v140
	v_mad_i64_i32 v[144:145], s[0:1], v142, s13, v[80:81]
	global_load_ushort v146, v[144:145], off
	global_load_ushort v148, v[144:145], off offset:32
	global_load_ushort v150, v[144:145], off offset:64
	global_load_ushort v152, v[144:145], off offset:96
	v_or_b32_e32 v154, 2, v54
	v_sub_u32_e32 v155, 0xfff, v154
	v_cndmask_b32_e32 v156, v155, v154, vcc
	v_add_u32_e32 v154, s14, v156
	v_mad_i64_i32 v[158:159], s[0:1], v154, s13, v[80:81]
	global_load_ushort v45, v[158:159], off
	global_load_ushort v47, v[158:159], off offset:32
	global_load_ushort v48, v[158:159], off offset:64
	global_load_ushort v50, v[158:159], off offset:96
	v_or_b32_e32 v160, 3, v54
	v_sub_u32_e32 v161, 0xfff, v160
	v_cndmask_b32_e32 v162, v161, v160, vcc
	v_add_u32_e32 v160, s14, v162
	v_mad_i64_i32 v[164:165], s[0:1], v160, s13, v[80:81]
	global_load_ushort v52, v[164:165], off
	global_load_ushort v54, v[164:165], off offset:32
	global_load_ushort v80, v[164:165], off offset:64
	global_load_ushort v81, v[164:165], off offset:96
	s_waitcnt vmcnt(31)
	v_cvt_pk_bf16_f32 v36, v57, v57
	v_cvt_pk_bf16_f32 v1, v58, v58
	v_cvt_pk_bf16_f32 v34, v59, v59
	s_waitcnt vmcnt(30)
	v_cvt_pk_bf16_f32 v2, v68, v68
	v_cvt_pk_bf16_f32 v4, v69, v69
	v_cvt_pk_bf16_f32 v3, v70, v71
	v_perm_b32 v2, v4, v2, s12
	v_cvt_pk_bf16_f32 v0, v56, v56
	v_perm_b32 v1, v34, v1, s12
	v_perm_b32 v0, v36, v0, s12
	s_waitcnt vmcnt(29)
	v_cvt_pk_bf16_f32 v40, v73, v73
	v_cvt_pk_bf16_f32 v5, v74, v74
	v_cvt_pk_bf16_f32 v38, v75, v75
	s_waitcnt vmcnt(28)
	v_cvt_pk_bf16_f32 v6, v76, v76
	v_cvt_pk_bf16_f32 v8, v77, v77
	v_cvt_pk_bf16_f32 v7, v78, v79
	v_perm_b32 v6, v8, v6, s12
	v_mfma_f32_16x16x32_bf16 v[0:3], v[60:63], v[0:3], 0
	v_cvt_pk_bf16_f32 v4, v72, v72
	v_perm_b32 v5, v38, v5, s12
	v_perm_b32 v4, v40, v4, s12
	s_nop 1
	v_mfma_f32_16x16x32_bf16 v[0:3], v[64:67], v[4:7], v[0:3]
	s_waitcnt vmcnt(27)
	v_cvt_pk_bf16_f32 v40, v87, v87
	v_cvt_pk_bf16_f32 v5, v88, v88
	v_cvt_pk_bf16_f32 v6, v89, v89
	s_waitcnt vmcnt(26)
	v_cvt_pk_bf16_f32 v7, v92, v92
	v_cvt_pk_bf16_f32 v10, v93, v93
	v_perm_b32 v5, v6, v5, s12
	v_perm_b32 v7, v10, v7, s12
	v_cvt_pk_bf16_f32 v6, v90, v91
	v_cvt_pk_bf16_f32 v4, v86, v86
	v_perm_b32 v4, v40, v4, s12
	s_nop 1
	v_mfma_f32_16x16x32_bf16 v[4:7], v[60:63], v[4:7], 0
	s_waitcnt vmcnt(25)
	v_cvt_pk_bf16_f32 v8, v94, v94
	v_cvt_pk_bf16_f32 v42, v95, v95
	v_cvt_pk_bf16_f32 v9, v96, v96
	v_cvt_pk_bf16_f32 v10, v97, v97
	s_waitcnt vmcnt(24)
	v_cvt_pk_bf16_f32 v11, v100, v100
	v_cvt_pk_bf16_f32 v36, v101, v101
	v_perm_b32 v9, v10, v9, s12
	v_perm_b32 v8, v42, v8, s12
	v_perm_b32 v11, v36, v11, s12
	v_cvt_pk_bf16_f32 v10, v98, v99
	s_nop 1
	v_mfma_f32_16x16x32_bf16 v[4:7], v[64:67], v[8:11], v[4:7]
	s_waitcnt vmcnt(23)
	v_cvt_pk_bf16_f32 v42, v103, v103
	v_cvt_pk_bf16_f32 v9, v104, v104
	v_cvt_pk_bf16_f32 v10, v105, v105
	s_waitcnt vmcnt(22)
	v_cvt_pk_bf16_f32 v11, v108, v108
	v_cvt_pk_bf16_f32 v36, v109, v109
	v_perm_b32 v9, v10, v9, s12
	v_perm_b32 v11, v36, v11, s12
	v_cvt_pk_bf16_f32 v10, v106, v107
	v_cvt_pk_bf16_f32 v8, v102, v102
	v_perm_b32 v8, v42, v8, s12
	s_nop 1
	v_mfma_f32_16x16x32_bf16 v[8:11], v[60:63], v[8:11], 0
	s_waitcnt vmcnt(21)
	v_cvt_pk_bf16_f32 v44, v111, v111
	v_cvt_pk_bf16_f32 v35, v112, v112
	v_cvt_pk_bf16_f32 v36, v113, v113
	v_perm_b32 v35, v36, v35, s12
	s_waitcnt vmcnt(20)
	v_cvt_pk_bf16_f32 v36, v82, v83
	v_cvt_pk_bf16_f32 v34, v110, v110
	v_cvt_pk_bf16_f32 v37, v84, v84
	v_cvt_pk_bf16_f32 v40, v85, v85
	v_perm_b32 v34, v44, v34, s12
	v_perm_b32 v37, v40, v37, s12
	s_nop 1
	v_mfma_f32_16x16x32_bf16 v[8:11], v[64:67], v[34:37], v[8:11]
	s_add_i32 s2, s2, s3
	s_add_i32 s6, s6, s7
	s_add_i32 s8, s8, s9
	s_cmpk_lt_i32 s2, 0x400
	s_waitcnt vmcnt(19)
	v_cvt_pk_bf16_f32 v34, v116, v116
	v_cvt_pk_bf16_f32 v46, v117, v117
	v_cvt_pk_bf16_f32 v35, v118, v118
	v_cvt_pk_bf16_f32 v36, v119, v119
	s_waitcnt vmcnt(18)
	v_cvt_pk_bf16_f32 v37, v122, v122
	v_cvt_pk_bf16_f32 v40, v123, v123
	v_perm_b32 v35, v36, v35, s12
	v_perm_b32 v34, v46, v34, s12
	v_perm_b32 v37, v40, v37, s12
	v_cvt_pk_bf16_f32 v36, v120, v121
	s_nop 1
	v_mfma_f32_16x16x32_bf16 v[16:19], v[60:63], v[34:37], 0
	s_waitcnt vmcnt(17)
	v_cvt_pk_bf16_f32 v34, v124, v124
	v_cvt_pk_bf16_f32 v42, v125, v125
	v_cvt_pk_bf16_f32 v31, v126, v126
	v_cvt_pk_bf16_f32 v30, v127, v127
	s_waitcnt vmcnt(16)
	v_cvt_pk_bf16_f32 v36, v128, v128
	v_cvt_pk_bf16_f32 v38, v129, v129
	v_perm_b32 v35, v30, v31, s12
	v_perm_b32 v34, v42, v34, s12
	v_cvt_pk_bf16_f32 v37, v130, v131
	v_perm_b32 v36, v38, v36, s12
	s_nop 1
	v_mfma_f32_16x16x32_bf16 v[12:15], v[64:67], v[34:37], v[16:19]
	s_waitcnt vmcnt(15)
	v_lshlrev_b32_e32 v31, 16, v55
	v_add_f32_e32 v0, v0, v31
	v_cvt_pk_bf16_f32 v0, v0, v0
	global_store_short_d16_hi v[114:115], v0, off
	s_waitcnt vmcnt(15)
	v_lshlrev_b32_e32 v0, 16, v132
	v_add_f32_e32 v0, v4, v0
	v_cvt_pk_bf16_f32 v0, v0, v0
	global_store_short_d16_hi v[114:115], v0, off offset:32
	s_waitcnt vmcnt(15)
	v_lshlrev_b32_e32 v0, 16, v134
	v_add_f32_e32 v0, v8, v0
	v_cvt_pk_bf16_f32 v0, v0, v0
	global_store_short_d16_hi v[114:115], v0, off offset:64
	s_waitcnt vmcnt(15)
	v_lshlrev_b32_e32 v0, 16, v136
	v_add_f32_e32 v0, v12, v0
	v_cvt_pk_bf16_f32 v0, v0, v0
	global_store_short_d16_hi v[114:115], v0, off offset:96
	s_waitcnt vmcnt(15)
	v_lshlrev_b32_e32 v0, 16, v146
	v_add_f32_e32 v0, v1, v0
	v_cvt_pk_bf16_f32 v0, v0, v0
	global_store_short_d16_hi v[144:145], v0, off
	s_waitcnt vmcnt(15)
	v_lshlrev_b32_e32 v0, 16, v148
	v_add_f32_e32 v0, v5, v0
	v_cvt_pk_bf16_f32 v0, v0, v0
	global_store_short_d16_hi v[144:145], v0, off offset:32
	s_waitcnt vmcnt(15)
	v_lshlrev_b32_e32 v0, 16, v150
	v_add_f32_e32 v0, v9, v0
	v_cvt_pk_bf16_f32 v0, v0, v0
	global_store_short_d16_hi v[144:145], v0, off offset:64
	s_waitcnt vmcnt(15)
	v_lshlrev_b32_e32 v0, 16, v152
	v_add_f32_e32 v0, v13, v0
	v_cvt_pk_bf16_f32 v0, v0, v0
	global_store_short_d16_hi v[144:145], v0, off offset:96
	s_waitcnt vmcnt(15)
	v_lshlrev_b32_e32 v4, 16, v45
	v_add_f32_e32 v2, v2, v4
	v_cvt_pk_bf16_f32 v2, v2, v2
	global_store_short_d16_hi v[158:159], v2, off
	s_waitcnt vmcnt(15)
	v_lshlrev_b32_e32 v2, 16, v47
	v_add_f32_e32 v2, v6, v2
	v_cvt_pk_bf16_f32 v2, v2, v2
	global_store_short_d16_hi v[158:159], v2, off offset:32
	s_waitcnt vmcnt(15)
	v_lshlrev_b32_e32 v2, 16, v48
	v_add_f32_e32 v2, v10, v2
	v_cvt_pk_bf16_f32 v2, v2, v2
	global_store_short_d16_hi v[158:159], v2, off offset:64
	s_waitcnt vmcnt(15)
	v_lshlrev_b32_e32 v2, 16, v50
	v_add_f32_e32 v2, v14, v2
	v_cvt_pk_bf16_f32 v2, v2, v2
	global_store_short_d16_hi v[158:159], v2, off offset:96
	s_waitcnt vmcnt(15)
	v_lshlrev_b32_e32 v2, 16, v52
	v_add_f32_e32 v2, v3, v2
	v_cvt_pk_bf16_f32 v2, v2, v2
	global_store_short_d16_hi v[164:165], v2, off
	s_waitcnt vmcnt(15)
	v_lshlrev_b32_e32 v2, 16, v54
	v_add_f32_e32 v2, v7, v2
	v_cvt_pk_bf16_f32 v2, v2, v2
	global_store_short_d16_hi v[164:165], v2, off offset:32
	s_waitcnt vmcnt(15)
	v_lshlrev_b32_e32 v2, 16, v80
	v_add_f32_e32 v2, v11, v2
	v_cvt_pk_bf16_f32 v2, v2, v2
	global_store_short_d16_hi v[164:165], v2, off offset:64
	s_waitcnt vmcnt(15)
	v_lshlrev_b32_e32 v2, 16, v81
	v_add_f32_e32 v2, v15, v2
	v_cvt_pk_bf16_f32 v2, v2, v2
	global_store_short_d16_hi v[164:165], v2, off offset:96
	s_cbranch_scc1 .LBB0_1291

.LBB0_2777:
	s_and_b32 s19, s20, 0x7c0
	s_ashr_i32 s18, s2, 5
	s_and_b32 s31, s22, 0xfffff000
	v_add_u32_e32 v108, s19, v1
	s_and_b32 s0, s18, 1
	s_addk_i32 s31, 0x1000
	v_add_u32_e32 v110, 0x800, v108
	s_cmp_eq_u32 s0, 0
	v_or_b32_e32 v111, v110, v0
	v_or_b32_e32 v112, v110, v18
	v_sub_u32_e32 v114, 0xfff, v111
	s_cselect_b64 vcc, -1, 0
	s_ashr_i32 s19, s18, 31
	v_sub_u32_e32 v115, 0xfff, v112
	v_or_b32_e32 v116, 1, v112
	v_or_b32_e32 v117, 2, v112
	v_or_b32_e32 v118, 3, v112
	v_cndmask_b32_e32 v113, v114, v111, vcc
	s_lshl_b64 s[18:19], s[18:19], 14
	v_cndmask_b32_e32 v110, v115, v112, vcc
	v_sub_u32_e32 v111, 0xfff, v116
	v_sub_u32_e32 v119, 0xfff, v117
	v_sub_u32_e32 v107, 0xfff, v118
	v_add_u32_e32 v108, s31, v113
	v_lshl_add_u64 v[112:113], v[4:5], 0, s[18:19]
	v_cndmask_b32_e32 v114, v111, v116, vcc
	v_cndmask_b32_e32 v115, v119, v117, vcc
	v_cndmask_b32_e32 v111, v107, v118, vcc
	v_add_co_u32_e32 v116, vcc, s24, v112
	s_and_b32 s33, s2, 0xc0
	s_nop 0
	v_addc_co_u32_e32 v117, vcc, 0, v113, vcc
	v_add_co_u32_e32 v118, vcc, s28, v112
	s_lshl_b32 s34, s0, 9
	s_nop 0
	v_addc_co_u32_e32 v119, vcc, 0, v113, vcc
	s_lshl_b32 s0, s33, 1
	v_add_u32_e32 v120, s31, v110
	v_mad_i64_i32 v[122:123], s[18:19], v108, s25, v[6:7]
	v_add_co_u32_e32 v124, vcc, s29, v112
	global_load_dwordx4 v[126:129], v[112:113], off offset:16
	global_load_dwordx4 v[130:133], v[112:113], off
	global_load_dwordx4 v[134:137], v[112:113], off offset:128
	global_load_dwordx4 v[138:141], v[112:113], off offset:144
	v_lshl_add_u64 v[142:143], v[112:113], 0, s[6:7]
	v_lshl_add_u64 v[144:145], v[112:113], 0, s[8:9]
	v_lshl_add_u64 v[146:147], v[112:113], 0, s[10:11]
	v_lshl_add_u64 v[148:149], v[112:113], 0, s[12:13]
	v_lshl_add_u64 v[150:151], v[112:113], 0, s[14:15]
	v_addc_co_u32_e32 v125, vcc, 0, v113, vcc
	v_lshl_add_u64 v[152:153], v[112:113], 0, s[16:17]
	v_lshl_add_u64 v[112:113], v[122:123], 0, s[0:1]
	v_add_u32_e32 v121, s31, v114
	v_add_u32_e32 v122, s31, v115
	global_load_dwordx4 v[154:157], v[142:143], off offset:16
	global_load_dwordx4 v[158:161], v[116:117], off offset:128
	global_load_dwordx4 v[114:117], v[118:119], off offset:-4096
	global_load_dwordx4 v[162:165], v[118:119], off
	global_load_dwordx4 v[166:169], v[144:145], off offset:16
	global_load_dwordx4 v[142:145], v[146:147], off offset:16
	global_load_dwordx4 v[170:173], v[118:119], off offset:128
	global_load_dwordx4 v[174:177], v[148:149], off offset:16
	global_load_dwordx4 v[146:149], v[150:151], off offset:16
	global_load_dwordx4 v[178:181], v[124:125], off
	global_load_dwordx4 v[182:185], v[124:125], off offset:128
	global_load_dwordx4 v[186:189], v[152:153], off offset:16
	v_lshl_add_u64 v[118:119], v[112:113], 0, v[2:3]
	v_lshl_add_u64 v[112:113], v[118:119], 0, s[4:5]
	v_add_co_u32_e32 v124, vcc, s24, v118
	s_add_u32 s33, s42, s34
	s_nop 0
	v_addc_co_u32_e32 v125, vcc, 0, v119, vcc
	global_load_dwordx4 v[150:153], v[124:125], off offset:800
	global_load_dwordx4 v[190:193], v[112:113], off offset:64
	s_addc_u32 s19, s43, 0
	s_add_u32 s18, s33, s0
	s_addc_u32 s19, s19, 0
	v_lshl_add_u64 v[112:113], s[18:19], 0, v[8:9]
	v_add_u32_e32 v107, s31, v111
	v_mad_i64_i32 v[110:111], s[18:19], v120, s30, v[112:113]
	v_mad_i64_i32 v[118:119], s[18:19], v121, s30, v[112:113]
	v_mad_i64_i32 v[120:121], s[18:19], v122, s30, v[112:113]
	v_mad_i64_i32 v[124:125], s[18:19], v107, s30, v[112:113]
	global_load_ushort v107, v[110:111], off
	global_load_ushort v112, v[110:111], off offset:32
	global_load_ushort v113, v[110:111], off offset:64
	global_load_ushort v194, v[110:111], off offset:96
	global_load_ushort v195, v[118:119], off
	global_load_ushort v196, v[118:119], off offset:32
	global_load_ushort v197, v[118:119], off offset:64
	global_load_ushort v198, v[118:119], off offset:96
	global_load_ushort v199, v[120:121], off
	global_load_ushort v200, v[120:121], off offset:32
	global_load_ushort v201, v[120:121], off offset:64
	global_load_ushort v202, v[120:121], off offset:96
	global_load_ushort v203, v[124:125], off
	global_load_ushort v204, v[124:125], off offset:32
	global_load_ushort v205, v[124:125], off offset:64
	global_load_ushort v108, v[124:125], off offset:96
	s_add_i32 s2, s2, s3
	s_add_i32 s20, s20, s21
	s_add_i32 s22, s22, s23
	s_cmpk_lt_i32 s2, 0x400
	s_waitcnt vmcnt(33)
	v_cvt_pk_bf16_f32 v23, v128, v129
	v_cvt_pk_bf16_f32 v22, v126, v127
	s_waitcnt vmcnt(32)
	v_cvt_pk_bf16_f32 v21, v132, v133
	v_cvt_pk_bf16_f32 v20, v130, v131
	s_waitcnt vmcnt(30)
	v_cvt_pk_bf16_f32 v27, v140, v141
	v_cvt_pk_bf16_f32 v26, v138, v139
	v_cvt_pk_bf16_f32 v25, v136, v137
	v_cvt_pk_bf16_f32 v24, v134, v135
	s_waitcnt vmcnt(27)
	v_cvt_pk_bf16_f32 v28, v114, v114
	v_cvt_pk_bf16_f32 v30, v115, v115
	v_cvt_pk_bf16_f32 v29, v116, v116
	v_cvt_pk_bf16_f32 v31, v117, v117
	v_cvt_pk_bf16_f32 v32, v154, v154
	v_cvt_pk_bf16_f32 v33, v155, v155
	v_cvt_pk_bf16_f32 v34, v156, v156
	v_cvt_pk_bf16_f32 v35, v157, v157
	v_cvt_pk_bf16_f32 v36, v158, v158
	v_cvt_pk_bf16_f32 v37, v159, v159
	v_cvt_pk_bf16_f32 v38, v160, v160
	v_cvt_pk_bf16_f32 v39, v161, v161
	s_waitcnt vmcnt(25)
	v_cvt_pk_bf16_f32 v40, v166, v166
	v_cvt_pk_bf16_f32 v41, v167, v167
	v_cvt_pk_bf16_f32 v42, v168, v168
	v_cvt_pk_bf16_f32 v43, v169, v169
	v_cvt_pk_bf16_f32 v44, v162, v162
	v_cvt_pk_bf16_f32 v45, v163, v163
	v_cvt_pk_bf16_f32 v46, v164, v164
	v_cvt_pk_bf16_f32 v47, v165, v165
	s_waitcnt vmcnt(24)
	v_cvt_pk_bf16_f32 v48, v142, v142
	v_cvt_pk_bf16_f32 v49, v143, v143
	v_cvt_pk_bf16_f32 v50, v144, v144
	v_cvt_pk_bf16_f32 v51, v145, v145
	v_perm_b32 v29, v31, v29, s27
	v_perm_b32 v28, v30, v28, s27
	v_perm_b32 v31, v35, v34, s27
	v_perm_b32 v30, v33, v32, s27
	v_perm_b32 v33, v39, v38, s27
	v_perm_b32 v32, v37, v36, s27
	v_perm_b32 v37, v47, v46, s27
	v_perm_b32 v36, v45, v44, s27
	v_perm_b32 v39, v51, v50, s27
	v_perm_b32 v38, v49, v48, s27
	s_waitcnt vmcnt(20)
	v_cvt_pk_bf16_f32 v45, v180, v181
	v_cvt_pk_bf16_f32 v44, v178, v179
	v_cvt_pk_bf16_f32 v47, v148, v149
	s_waitcnt vmcnt(17)
	v_mfma_f32_16x16x32_bf16 v[20:23], v[150:153], v[20:23], 0
	v_cvt_pk_bf16_f32 v46, v146, v147
	v_mfma_f32_16x16x32_bf16 v[28:31], v[150:153], v[28:31], 0
	v_mfma_f32_16x16x32_bf16 v[36:39], v[150:153], v[36:39], 0
	v_mfma_f32_16x16x32_bf16 v[44:47], v[150:153], v[44:47], 0
	v_perm_b32 v35, v43, v42, s27
	v_perm_b32 v34, v41, v40, s27
	v_cvt_pk_bf16_f32 v41, v172, v173
	v_cvt_pk_bf16_f32 v40, v170, v171
	v_cvt_pk_bf16_f32 v43, v176, v177
	v_cvt_pk_bf16_f32 v42, v174, v175
	v_cvt_pk_bf16_f32 v49, v184, v185
	v_cvt_pk_bf16_f32 v48, v182, v183
	v_cvt_pk_bf16_f32 v51, v188, v189
	v_cvt_pk_bf16_f32 v50, v186, v187
	s_waitcnt vmcnt(16)
	v_mfma_f32_16x16x32_bf16 v[20:23], v[190:193], v[24:27], v[20:23]
	s_waitcnt vmcnt(15)
	v_lshlrev_b32_e32 v19, 16, v107
	s_waitcnt vmcnt(14)
	v_lshlrev_b32_e32 v52, 16, v112
	s_waitcnt vmcnt(13)
	v_lshlrev_b32_e32 v53, 16, v113
	v_mfma_f32_16x16x32_bf16 v[24:27], v[190:193], v[32:35], v[28:31]
	s_waitcnt vmcnt(12)
	v_lshlrev_b32_e32 v54, 16, v194
	s_waitcnt vmcnt(11)
	v_lshlrev_b32_e32 v55, 16, v195
	s_waitcnt vmcnt(10)
	v_lshlrev_b32_e32 v56, 16, v196
	v_mfma_f32_16x16x32_bf16 v[28:31], v[190:193], v[40:43], v[36:39]
	s_waitcnt vmcnt(9)
	v_lshlrev_b32_e32 v57, 16, v197
	s_waitcnt vmcnt(8)
	v_lshlrev_b32_e32 v58, 16, v198
	s_waitcnt vmcnt(7)
	v_lshlrev_b32_e32 v59, 16, v199
	v_mfma_f32_16x16x32_bf16 v[32:35], v[190:193], v[48:51], v[44:47]
	s_waitcnt vmcnt(6)
	v_lshlrev_b32_e32 v60, 16, v200
	s_waitcnt vmcnt(5)
	v_lshlrev_b32_e32 v61, 16, v201
	s_waitcnt vmcnt(4)
	v_lshlrev_b32_e32 v62, 16, v202
	s_waitcnt vmcnt(3)
	v_lshlrev_b32_e32 v63, 16, v203
	s_waitcnt vmcnt(2)
	v_lshlrev_b32_e32 v36, 16, v204
	s_waitcnt vmcnt(1)
	v_lshlrev_b32_e32 v37, 16, v205
	s_waitcnt vmcnt(0)
	v_lshlrev_b32_e32 v38, 16, v108
	v_add_f32_e32 v19, v20, v19
	v_add_f32_e32 v20, v24, v52
	v_add_f32_e32 v24, v28, v53
	v_add_f32_e32 v28, v32, v54
	v_add_f32_e32 v21, v21, v55
	v_add_f32_e32 v25, v25, v56
	v_add_f32_e32 v29, v29, v57
	v_add_f32_e32 v32, v33, v58
	v_add_f32_e32 v22, v22, v59
	v_add_f32_e32 v26, v26, v60
	v_add_f32_e32 v30, v30, v61
	v_add_f32_e32 v33, v34, v62
	v_add_f32_e32 v23, v23, v63
	v_add_f32_e32 v27, v27, v36
	v_add_f32_e32 v31, v31, v37
	v_add_f32_e32 v34, v35, v38
	v_cvt_pk_bf16_f32 v19, v19, v19
	v_cvt_pk_bf16_f32 v20, v20, v20
	v_cvt_pk_bf16_f32 v24, v24, v24
	v_cvt_pk_bf16_f32 v28, v28, v28
	v_cvt_pk_bf16_f32 v21, v21, v21
	v_cvt_pk_bf16_f32 v25, v25, v25
	v_cvt_pk_bf16_f32 v29, v29, v29
	v_cvt_pk_bf16_f32 v32, v32, v32
	v_cvt_pk_bf16_f32 v22, v22, v22
	v_cvt_pk_bf16_f32 v26, v26, v26
	v_cvt_pk_bf16_f32 v30, v30, v30
	v_cvt_pk_bf16_f32 v33, v33, v33
	v_cvt_pk_bf16_f32 v23, v23, v23
	v_cvt_pk_bf16_f32 v27, v27, v27
	v_cvt_pk_bf16_f32 v31, v31, v31
	v_cvt_pk_bf16_f32 v34, v34, v34
	global_store_short_d16_hi v[110:111], v19, off
	global_store_short_d16_hi v[110:111], v20, off offset:32
	global_store_short_d16_hi v[110:111], v24, off offset:64
	global_store_short_d16_hi v[110:111], v28, off offset:96
	global_store_short_d16_hi v[118:119], v21, off
	global_store_short_d16_hi v[118:119], v25, off offset:32
	global_store_short_d16_hi v[118:119], v29, off offset:64
	global_store_short_d16_hi v[118:119], v32, off offset:96
	global_store_short_d16_hi v[120:121], v22, off
	global_store_short_d16_hi v[120:121], v26, off offset:32
	global_store_short_d16_hi v[120:121], v30, off offset:64
	global_store_short_d16_hi v[120:121], v33, off offset:96
	global_store_short_d16_hi v[124:125], v23, off
	global_store_short_d16_hi v[124:125], v27, off offset:32
	global_store_short_d16_hi v[124:125], v31, off offset:64
	global_store_short_d16_hi v[124:125], v34, off offset:96
	s_cbranch_scc1 .LBB0_2777
